# MLA attention: all 8 V-fragment LDS reads of a tile issued right after the QK MFMAs into spare registers, PV = 16 back-to-back MFMAs without LDS waits
# speedup vs baseline: 1.0050x; 1.0044x over previous
.LBB0_360:
	v_exp_f32_e32 v144, v144
	v_exp_f32_e32 v145, v145
	v_exp_f32_e32 v146, v146
	v_exp_f32_e32 v147, v147
	v_add_f32_e32 v190, 0, v144
	v_exp_f32_e32 v191, v140
	v_add_f32_e32 v190, v145, v190
	v_add_f32_e32 v190, v146, v190
	v_add_f32_e32 v190, v147, v190
	v_add_f32_e32 v140, v191, v190
	v_exp_f32_e32 v190, v141
	v_exp_f32_e32 v192, v142
	v_exp_f32_e32 v143, v143
	v_exp_f32_e32 v136, v136
	v_add_f32_e32 v140, v190, v140
	v_exp_f32_e32 v137, v137
	v_add_f32_e32 v140, v192, v140
	v_exp_f32_e32 v138, v138
	v_add_f32_e32 v140, v143, v140
	v_exp_f32_e32 v139, v139
	v_add_f32_e32 v165, v140, v165
	v_cvt_pk_bf16_f32 v140, v144, v145
	v_add_f32_e32 v144, 0, v136
	v_exp_f32_e32 v145, v132
	v_add_f32_e32 v144, v137, v144
	v_add_f32_e32 v144, v138, v144
	v_add_f32_e32 v144, v139, v144
	v_add_f32_e32 v132, v145, v144
	v_exp_f32_e32 v144, v133
	v_cvt_pk_bf16_f32 v141, v146, v147
	v_exp_f32_e32 v146, v134
	v_exp_f32_e32 v135, v135
	v_add_f32_e32 v132, v144, v132
	v_cvt_pk_bf16_f32 v134, v145, v144
	v_add_f32_e32 v132, v146, v132
	v_add_f32_e32 v132, v135, v132
	v_cvt_pk_bf16_f32 v142, v191, v190
	v_add_f32_e32 v160, v132, v160
	v_cvt_pk_bf16_f32 v132, v136, v137
	v_cvt_pk_bf16_f32 v143, v192, v143
	v_cvt_pk_bf16_f32 v133, v138, v139
	v_cvt_pk_bf16_f32 v135, v146, v135
	s_waitcnt lgkmcnt(0)
	v_mfma_f32_16x16x32_bf16 v[84:87], v[214:217], v[140:143], v[84:87]
	v_mfma_f32_16x16x32_bf16 v[64:67], v[214:217], v[132:135], v[64:67]
	v_mfma_f32_16x16x32_bf16 v[108:111], v[218:221], v[140:143], v[108:111]
	v_mfma_f32_16x16x32_bf16 v[96:99], v[218:221], v[132:135], v[96:99]
	v_mfma_f32_16x16x32_bf16 v[104:107], v[222:225], v[140:143], v[104:107]
	v_mfma_f32_16x16x32_bf16 v[92:95], v[222:225], v[132:135], v[92:95]
	v_mfma_f32_16x16x32_bf16 v[80:83], v[226:229], v[140:143], v[80:83]
	v_mfma_f32_16x16x32_bf16 v[60:63], v[226:229], v[132:135], v[60:63]
	v_mfma_f32_16x16x32_bf16 v[100:103], v[230:233], v[140:143], v[100:103]
	v_mfma_f32_16x16x32_bf16 v[88:91], v[230:233], v[132:135], v[88:91]
	v_mfma_f32_16x16x32_bf16 v[76:79], v[234:237], v[140:143], v[76:79]
	v_mfma_f32_16x16x32_bf16 v[56:59], v[234:237], v[132:135], v[56:59]
	v_mfma_f32_16x16x32_bf16 v[72:75], v[242:245], v[140:143], v[72:75]
	v_mfma_f32_16x16x32_bf16 v[52:55], v[242:245], v[132:135], v[52:55]
	v_mfma_f32_16x16x32_bf16 v[68:71], v[246:249], v[140:143], v[68:71]
	v_mfma_f32_16x16x32_bf16 v[48:51], v[246:249], v[132:135], v[48:51]
	s_add_i32 s4, s4, 1
	s_cmp_lg_u32 s4, 8
	s_barrier
	s_cbranch_scc0 .LBB0_365
.LBB0_361:
	s_add_i32 s5, s4, -1
	s_bitcmp1_b32 s5, 0
	s_cselect_b32 s30, 0x5c00, 0
	s_bitcmp1_b32 s4, 0
	s_cselect_b32 s6, 0x5c00, 0
	v_add_u32_e32 v212, s30, v185
	v_add_u32_e32 v211, 0x1a00, v212
	v_add_u32_e32 v205, v211, v210
	v_add_u32_e32 v204, v212, v210
	ds_read_b128 v[136:139], v205
	ds_read_b128 v[140:143], v204
	ds_read_b128 v[144:147], v204 offset:64
	v_lshlrev_b32_e32 v132, 1, v178
	v_lshlrev_b32_e32 v133, 1, v152
	v_add3_u32 v132, s6, v132, v133
	s_waitcnt vmcnt(4)
	ds_write_b128 v132, v[112:115]
	v_lshlrev_b32_e32 v112, 1, v179
	v_lshlrev_b32_e32 v113, 1, v154
	v_add3_u32 v112, s6, v112, v113
	s_waitcnt vmcnt(3)
	ds_write_b128 v112, v[116:119]
	v_lshlrev_b32_e32 v112, 1, v180
	v_lshlrev_b32_e32 v113, 1, v156
	v_add3_u32 v112, s6, v112, v113
	s_waitcnt vmcnt(2)
	ds_write_b128 v112, v[128:131]
	v_lshlrev_b32_e32 v112, 1, v181
	v_lshlrev_b32_e32 v113, 1, v158
	v_add3_u32 v112, s6, v112, v113
	s_waitcnt vmcnt(1)
	ds_write_b128 v112, v[124:127] offset:13312
	v_lshlrev_b32_e32 v112, 1, v182
	v_lshlrev_b32_e32 v113, 1, v164
	s_min_u32 s5, s5, 5
	v_add3_u32 v112, s6, v112, v113
	s_lshl_b32 s6, s5, 5
	s_add_i32 s31, s6, 64
	s_waitcnt vmcnt(0)
	ds_write_b128 v112, v[120:123] offset:13312
	v_add_u32_e32 v112, s31, v161
	v_add_u32_e32 v114, s31, v174
	v_add_u32_e32 v120, s31, v175
	v_mad_i64_i32 v[112:113], s[6:7], v112, s18, v[168:169]
	v_mad_i64_i32 v[116:117], s[6:7], v114, s18, v[170:171]
	v_mad_i64_i32 v[120:121], s[6:7], v120, s18, v[172:173]
	s_lshl_b32 s36, s5, 6
	global_load_dwordx4 v[112:115], v[112:113], off
	s_nop 0
	global_load_dwordx4 v[116:119], v[116:117], off
	v_lshl_add_u64 v[122:123], v[162:163], 0, s[36:37]
	global_load_dwordx4 v[128:131], v[120:121], off
	global_load_dwordx4 v[124:127], v[122:123], off offset:128
	v_lshl_add_u64 v[120:121], v[166:167], 0, s[36:37]
	global_load_dwordx4 v[120:123], v[120:121], off offset:128
	v_xor_b32_e32 v132, 0x80000000, v187
	v_mov_b32_e32 v133, v132
	v_mov_b32_e32 v134, v132
	v_mov_b32_e32 v135, v132
	v_xor_b32_e32 v190, 0x80000000, v186
	v_mov_b32_e32 v191, v190
	v_mov_b32_e32 v192, v190
	v_mov_b32_e32 v193, v190
	s_waitcnt lgkmcnt(6)
	v_mfma_f32_16x16x32_bf16 v[194:197], v[140:143], v[40:43], v[132:135]
	v_mfma_f32_16x16x32_bf16 v[140:143], v[140:143], v[44:47], v[190:193]
	ds_read_b128 v[198:201], v205 offset:64
	v_mfma_f32_16x16x32_bf16 v[132:135], v[136:139], v[40:43], v[132:135]
	v_mfma_f32_16x16x32_bf16 v[136:139], v[136:139], v[44:47], v[190:193]
	s_nop 2
	ds_read_b128 v[190:193], v204 offset:128
	s_waitcnt lgkmcnt(2)
	v_mfma_f32_16x16x32_bf16 v[140:143], v[144:147], v[36:39], v[140:143]
	v_mfma_f32_16x16x32_bf16 v[194:197], v[144:147], v[32:35], v[194:197]
	ds_read_b128 v[144:147], v205 offset:128
	s_waitcnt lgkmcnt(2)
	v_mfma_f32_16x16x32_bf16 v[132:135], v[198:201], v[32:35], v[132:135]
	v_mfma_f32_16x16x32_bf16 v[136:139], v[198:201], v[36:39], v[136:139]
	ds_read_b128 v[198:201], v204 offset:192
	s_waitcnt lgkmcnt(2)
	v_mfma_f32_16x16x32_bf16 v[140:143], v[190:193], v[28:31], v[140:143]
	v_mfma_f32_16x16x32_bf16 v[194:197], v[190:193], v[24:27], v[194:197]
	ds_read_b128 v[190:193], v205 offset:192
	s_waitcnt lgkmcnt(2)
	v_mfma_f32_16x16x32_bf16 v[132:135], v[144:147], v[24:27], v[132:135]
	v_mfma_f32_16x16x32_bf16 v[136:139], v[144:147], v[28:31], v[136:139]
	ds_read_b128 v[144:147], v204 offset:256
	s_waitcnt lgkmcnt(2)
	v_mfma_f32_16x16x32_bf16 v[140:143], v[198:201], v[20:23], v[140:143]
	v_mfma_f32_16x16x32_bf16 v[194:197], v[198:201], v[16:19], v[194:197]
	ds_read_b128 v[198:201], v205 offset:256
	s_waitcnt lgkmcnt(2)
	v_mfma_f32_16x16x32_bf16 v[132:135], v[190:193], v[16:19], v[132:135]
	v_mfma_f32_16x16x32_bf16 v[136:139], v[190:193], v[20:23], v[136:139]
	ds_read_b128 v[190:193], v204 offset:320
	s_waitcnt lgkmcnt(2)
	v_mfma_f32_16x16x32_bf16 v[140:143], v[144:147], v[12:15], v[140:143]
	v_mfma_f32_16x16x32_bf16 v[194:197], v[144:147], v[4:7], v[194:197]
	ds_read_b128 v[204:207], v205 offset:320
	s_waitcnt lgkmcnt(2)
	v_mfma_f32_16x16x32_bf16 v[132:135], v[198:201], v[4:7], v[132:135]
	v_mfma_f32_16x16x32_bf16 v[198:201], v[198:201], v[12:15], v[136:139]
	s_waitcnt lgkmcnt(1)
	v_mfma_f32_16x16x32_bf16 v[144:147], v[190:193], v[0:3], v[194:197]
	v_mfma_f32_16x16x32_bf16 v[136:139], v[190:193], v[8:11], v[140:143]
	s_waitcnt lgkmcnt(0)
	v_mfma_f32_16x16x32_bf16 v[140:143], v[204:207], v[0:3], v[132:135]
	v_mfma_f32_16x16x32_bf16 v[132:135], v[204:207], v[8:11], v[198:201]
	v_lshlrev_b32_e32 v238, 1, v176
	v_add3_u32 v239, v211, v209, v238
	v_add3_u32 v238, v212, v208, v238
	v_add_u32_e32 v250, 0x3000, v238
	ds_read2_b64 v[214:217], v250 offset0:128 offset1:132
	v_add_u32_e32 v250, 0x3000, v239
	ds_read2_b64 v[218:221], v250 offset0:128 offset1:132
	v_add_u32_e32 v250, 0x3800, v238
	ds_read2_b64 v[222:225], v250 offset0:192 offset1:196
	v_add_u32_e32 v250, 0x4000, v238
	ds_read2_b64 v[226:229], v250 offset0:96 offset1:100
	v_add_u32_e32 v250, 0x4800, v238
	ds_read2_b64 v[230:233], v250 offset1:4
	ds_read2_b64 v[234:237], v250 offset0:160 offset1:164
	v_add_u32_e32 v250, 0x5000, v238
	ds_read2_b64 v[242:245], v250 offset0:64 offset1:68
	ds_read2_b64 v[246:249], v250 offset0:224 offset1:228
	v_max_f32_e32 v190, v145, v145
	v_max_f32_e32 v191, v144, v144
	v_max_f32_e32 v198, v137, v137
	v_max_f32_e32 v199, v136, v136
	v_max_f32_e32 v190, v191, v190
	v_max_f32_e32 v198, v199, v198
	v_max3_f32 v190, v190, v146, v147
	v_max3_f32 v198, v198, v138, v139
	v_max3_f32 v190, v190, v140, v141
	v_max3_f32 v198, v198, v132, v133
	v_max3_f32 v190, v190, v142, v143
	v_max3_f32 v198, v198, v134, v135
	v_mov_b32_e32 v191, v190
	v_mov_b32_e32 v199, v198
	s_nop 1
	v_permlane16_swap_b32_e32 v191, v190
	v_permlane16_swap_b32_e32 v199, v198
	v_max_f32_e32 v190, v190, v191
	v_max_f32_e32 v198, v198, v199
	v_mov_b32_e32 v191, v190
	v_mov_b32_e32 v199, v198
	s_nop 1
	v_permlane32_swap_b32_e32 v191, v190
	v_permlane32_swap_b32_e32 v199, v198
	v_max_f32_e32 v213, v190, v191
	v_max_f32_e32 v200, v198, v199
	v_cmp_lt_f32_e32 vcc, s79, v213
	s_cbranch_vccz .LBB0_363
	s_nop 0
	v_cndmask_b32_e32 v191, 0, v213, vcc
	v_exp_f32_e64 v190, -v191
	v_add_f32_e32 v187, v187, v191
	v_sub_f32_e32 v144, v144, v191
	v_sub_f32_e32 v145, v145, v191
	v_pk_mul_f32 v[70:71], v[70:71], v[190:191] op_sel_hi:[1,0]
	v_pk_mul_f32 v[68:69], v[68:69], v[190:191] op_sel_hi:[1,0]
	v_pk_mul_f32 v[74:75], v[74:75], v[190:191] op_sel_hi:[1,0]
	v_pk_mul_f32 v[72:73], v[72:73], v[190:191] op_sel_hi:[1,0]
	v_pk_mul_f32 v[78:79], v[78:79], v[190:191] op_sel_hi:[1,0]
	v_pk_mul_f32 v[76:77], v[76:77], v[190:191] op_sel_hi:[1,0]
	v_pk_mul_f32 v[102:103], v[102:103], v[190:191] op_sel_hi:[1,0]
	v_pk_mul_f32 v[100:101], v[100:101], v[190:191] op_sel_hi:[1,0]
	v_pk_mul_f32 v[82:83], v[82:83], v[190:191] op_sel_hi:[1,0]
	v_pk_mul_f32 v[80:81], v[80:81], v[190:191] op_sel_hi:[1,0]
	v_pk_mul_f32 v[106:107], v[106:107], v[190:191] op_sel_hi:[1,0]
	v_pk_mul_f32 v[104:105], v[104:105], v[190:191] op_sel_hi:[1,0]
	v_pk_mul_f32 v[110:111], v[110:111], v[190:191] op_sel_hi:[1,0]
	v_pk_mul_f32 v[108:109], v[108:109], v[190:191] op_sel_hi:[1,0]
	v_pk_mul_f32 v[86:87], v[86:87], v[190:191] op_sel_hi:[1,0]
	v_pk_mul_f32 v[84:85], v[84:85], v[190:191] op_sel_hi:[1,0]
	v_mul_f32_e32 v165, v165, v190
	v_sub_f32_e32 v146, v146, v191
	v_sub_f32_e32 v147, v147, v191
	v_sub_f32_e32 v140, v140, v191
	v_sub_f32_e32 v141, v141, v191
	v_sub_f32_e32 v142, v142, v191
	v_sub_f32_e32 v143, v143, v191

.LBB0_376:
	v_exp_f32_e32 v144, v144
	v_exp_f32_e32 v145, v145
	v_exp_f32_e32 v146, v146
	v_exp_f32_e32 v147, v147
	v_add_f32_e32 v190, 0, v144
	v_exp_f32_e32 v191, v140
	v_add_f32_e32 v190, v145, v190
	v_add_f32_e32 v190, v146, v190
	v_add_f32_e32 v190, v147, v190
	v_add_f32_e32 v140, v191, v190
	v_exp_f32_e32 v190, v141
	v_exp_f32_e32 v192, v142
	v_exp_f32_e32 v143, v143
	v_exp_f32_e32 v136, v136
	v_add_f32_e32 v140, v190, v140
	v_exp_f32_e32 v137, v137
	v_add_f32_e32 v140, v192, v140
	v_exp_f32_e32 v138, v138
	v_add_f32_e32 v140, v143, v140
	v_exp_f32_e32 v139, v139
	v_add_f32_e32 v165, v140, v165
	v_cvt_pk_bf16_f32 v140, v144, v145
	v_add_f32_e32 v144, 0, v136
	v_exp_f32_e32 v145, v132
	v_add_f32_e32 v144, v137, v144
	v_add_f32_e32 v144, v138, v144
	v_add_f32_e32 v144, v139, v144
	v_add_f32_e32 v132, v145, v144
	v_exp_f32_e32 v144, v133
	v_cvt_pk_bf16_f32 v141, v146, v147
	v_exp_f32_e32 v146, v134
	v_exp_f32_e32 v135, v135
	v_add_f32_e32 v132, v144, v132
	v_cvt_pk_bf16_f32 v134, v145, v144
	v_add_f32_e32 v132, v146, v132
	v_add_f32_e32 v132, v135, v132
	v_cvt_pk_bf16_f32 v142, v191, v190
	v_add_f32_e32 v160, v132, v160
	v_cvt_pk_bf16_f32 v132, v136, v137
	v_cvt_pk_bf16_f32 v143, v192, v143
	v_cvt_pk_bf16_f32 v133, v138, v139
	v_cvt_pk_bf16_f32 v135, v146, v135
	s_waitcnt lgkmcnt(0)
	v_mfma_f32_16x16x32_bf16 v[84:87], v[214:217], v[140:143], v[84:87]
	v_mfma_f32_16x16x32_bf16 v[64:67], v[214:217], v[132:135], v[64:67]
	v_mfma_f32_16x16x32_bf16 v[108:111], v[218:221], v[140:143], v[108:111]
	v_mfma_f32_16x16x32_bf16 v[96:99], v[218:221], v[132:135], v[96:99]
	v_mfma_f32_16x16x32_bf16 v[104:107], v[222:225], v[140:143], v[104:107]
	v_mfma_f32_16x16x32_bf16 v[92:95], v[222:225], v[132:135], v[92:95]
	v_mfma_f32_16x16x32_bf16 v[80:83], v[226:229], v[140:143], v[80:83]
	v_mfma_f32_16x16x32_bf16 v[60:63], v[226:229], v[132:135], v[60:63]
	v_mfma_f32_16x16x32_bf16 v[100:103], v[230:233], v[140:143], v[100:103]
	v_mfma_f32_16x16x32_bf16 v[88:91], v[230:233], v[132:135], v[88:91]
	v_mfma_f32_16x16x32_bf16 v[76:79], v[234:237], v[140:143], v[76:79]
	v_mfma_f32_16x16x32_bf16 v[56:59], v[234:237], v[132:135], v[56:59]
	v_mfma_f32_16x16x32_bf16 v[72:75], v[242:245], v[140:143], v[72:75]
	v_mfma_f32_16x16x32_bf16 v[52:55], v[242:245], v[132:135], v[52:55]
	v_mfma_f32_16x16x32_bf16 v[68:71], v[246:249], v[140:143], v[68:71]
	v_mfma_f32_16x16x32_bf16 v[48:51], v[246:249], v[132:135], v[48:51]
	s_add_i32 s4, s4, 1
	s_cmp_lg_u32 s4, 40
	s_barrier
	s_cbranch_scc0 .LBB0_381
.LBB0_377:
	s_add_i32 s5, s4, -1
	s_bitcmp1_b32 s5, 0
	s_cselect_b32 s30, 0x5c00, 0
	s_bitcmp1_b32 s4, 0
	s_cselect_b32 s6, 0x5c00, 0
	v_add_u32_e32 v212, s30, v185
	v_add_u32_e32 v211, 0x1a00, v212
	v_add_u32_e32 v205, v211, v210
	v_add_u32_e32 v204, v212, v210
	ds_read_b128 v[136:139], v205
	ds_read_b128 v[140:143], v204
	ds_read_b128 v[144:147], v204 offset:64
	v_lshlrev_b32_e32 v132, 1, v178
	v_lshlrev_b32_e32 v133, 1, v152
	v_add3_u32 v132, s6, v132, v133
	s_waitcnt vmcnt(4)
	ds_write_b128 v132, v[112:115]
	v_lshlrev_b32_e32 v112, 1, v179
	v_lshlrev_b32_e32 v113, 1, v154
	v_add3_u32 v112, s6, v112, v113
	s_waitcnt vmcnt(3)
	ds_write_b128 v112, v[116:119]
	v_lshlrev_b32_e32 v112, 1, v180
	v_lshlrev_b32_e32 v113, 1, v156
	v_add3_u32 v112, s6, v112, v113
	s_waitcnt vmcnt(2)
	ds_write_b128 v112, v[128:131]
	v_lshlrev_b32_e32 v112, 1, v181
	v_lshlrev_b32_e32 v113, 1, v158
	v_add3_u32 v112, s6, v112, v113
	s_waitcnt vmcnt(1)
	ds_write_b128 v112, v[124:127] offset:13312
	v_lshlrev_b32_e32 v112, 1, v182
	v_lshlrev_b32_e32 v113, 1, v164
	s_min_u32 s5, s5, 37
	v_add3_u32 v112, s6, v112, v113
	s_lshl_b32 s6, s5, 5
	s_add_i32 s31, s6, 64
	s_waitcnt vmcnt(0)
	ds_write_b128 v112, v[120:123] offset:13312
	v_add_u32_e32 v112, s31, v161
	v_add_u32_e32 v114, s31, v174
	v_add_u32_e32 v120, s31, v175
	v_mad_i64_i32 v[112:113], s[6:7], v112, s18, v[168:169]
	v_mad_i64_i32 v[116:117], s[6:7], v114, s18, v[170:171]
	v_mad_i64_i32 v[120:121], s[6:7], v120, s18, v[172:173]
	s_lshl_b32 s36, s5, 6
	global_load_dwordx4 v[112:115], v[112:113], off
	s_nop 0
	global_load_dwordx4 v[116:119], v[116:117], off
	v_lshl_add_u64 v[122:123], v[162:163], 0, s[36:37]
	global_load_dwordx4 v[128:131], v[120:121], off
	global_load_dwordx4 v[124:127], v[122:123], off offset:128
	v_lshl_add_u64 v[120:121], v[166:167], 0, s[36:37]
	global_load_dwordx4 v[120:123], v[120:121], off offset:128
	v_xor_b32_e32 v132, 0x80000000, v187
	v_mov_b32_e32 v133, v132
	v_mov_b32_e32 v134, v132
	v_mov_b32_e32 v135, v132
	v_xor_b32_e32 v190, 0x80000000, v186
	v_mov_b32_e32 v191, v190
	v_mov_b32_e32 v192, v190
	v_mov_b32_e32 v193, v190
	s_waitcnt lgkmcnt(6)
	v_mfma_f32_16x16x32_bf16 v[194:197], v[140:143], v[40:43], v[132:135]
	v_mfma_f32_16x16x32_bf16 v[140:143], v[140:143], v[44:47], v[190:193]
	ds_read_b128 v[198:201], v205 offset:64
	v_mfma_f32_16x16x32_bf16 v[132:135], v[136:139], v[40:43], v[132:135]
	v_mfma_f32_16x16x32_bf16 v[136:139], v[136:139], v[44:47], v[190:193]
	s_nop 2
	ds_read_b128 v[190:193], v204 offset:128
	s_waitcnt lgkmcnt(2)
	v_mfma_f32_16x16x32_bf16 v[140:143], v[144:147], v[36:39], v[140:143]
	v_mfma_f32_16x16x32_bf16 v[194:197], v[144:147], v[32:35], v[194:197]
	ds_read_b128 v[144:147], v205 offset:128
	s_waitcnt lgkmcnt(2)
	v_mfma_f32_16x16x32_bf16 v[132:135], v[198:201], v[32:35], v[132:135]
	v_mfma_f32_16x16x32_bf16 v[136:139], v[198:201], v[36:39], v[136:139]
	ds_read_b128 v[198:201], v204 offset:192
	s_waitcnt lgkmcnt(2)
	v_mfma_f32_16x16x32_bf16 v[140:143], v[190:193], v[28:31], v[140:143]
	v_mfma_f32_16x16x32_bf16 v[194:197], v[190:193], v[24:27], v[194:197]
	ds_read_b128 v[190:193], v205 offset:192
	s_waitcnt lgkmcnt(2)
	v_mfma_f32_16x16x32_bf16 v[132:135], v[144:147], v[24:27], v[132:135]
	v_mfma_f32_16x16x32_bf16 v[136:139], v[144:147], v[28:31], v[136:139]
	ds_read_b128 v[144:147], v204 offset:256
	s_waitcnt lgkmcnt(2)
	v_mfma_f32_16x16x32_bf16 v[140:143], v[198:201], v[20:23], v[140:143]
	v_mfma_f32_16x16x32_bf16 v[194:197], v[198:201], v[16:19], v[194:197]
	ds_read_b128 v[198:201], v205 offset:256
	s_waitcnt lgkmcnt(2)
	v_mfma_f32_16x16x32_bf16 v[132:135], v[190:193], v[16:19], v[132:135]
	v_mfma_f32_16x16x32_bf16 v[136:139], v[190:193], v[20:23], v[136:139]
	ds_read_b128 v[190:193], v204 offset:320
	s_waitcnt lgkmcnt(2)
	v_mfma_f32_16x16x32_bf16 v[140:143], v[144:147], v[12:15], v[140:143]
	v_mfma_f32_16x16x32_bf16 v[194:197], v[144:147], v[4:7], v[194:197]
	ds_read_b128 v[204:207], v205 offset:320
	s_waitcnt lgkmcnt(2)
	v_mfma_f32_16x16x32_bf16 v[132:135], v[198:201], v[4:7], v[132:135]
	v_mfma_f32_16x16x32_bf16 v[198:201], v[198:201], v[12:15], v[136:139]
	s_waitcnt lgkmcnt(1)
	v_mfma_f32_16x16x32_bf16 v[144:147], v[190:193], v[0:3], v[194:197]
	v_mfma_f32_16x16x32_bf16 v[136:139], v[190:193], v[8:11], v[140:143]
	s_waitcnt lgkmcnt(0)
	v_mfma_f32_16x16x32_bf16 v[140:143], v[204:207], v[0:3], v[132:135]
	v_mfma_f32_16x16x32_bf16 v[132:135], v[204:207], v[8:11], v[198:201]
	v_lshlrev_b32_e32 v238, 1, v176
	v_add3_u32 v239, v211, v209, v238
	v_add3_u32 v238, v212, v208, v238
	v_add_u32_e32 v250, 0x3000, v238
	ds_read2_b64 v[214:217], v250 offset0:128 offset1:132
	v_add_u32_e32 v250, 0x3000, v239
	ds_read2_b64 v[218:221], v250 offset0:128 offset1:132
	v_add_u32_e32 v250, 0x3800, v238
	ds_read2_b64 v[222:225], v250 offset0:192 offset1:196
	v_add_u32_e32 v250, 0x4000, v238
	ds_read2_b64 v[226:229], v250 offset0:96 offset1:100
	v_add_u32_e32 v250, 0x4800, v238
	ds_read2_b64 v[230:233], v250 offset1:4
	ds_read2_b64 v[234:237], v250 offset0:160 offset1:164
	v_add_u32_e32 v250, 0x5000, v238
	ds_read2_b64 v[242:245], v250 offset0:64 offset1:68
	ds_read2_b64 v[246:249], v250 offset0:224 offset1:228
	v_max_f32_e32 v190, v145, v145
	v_max_f32_e32 v191, v144, v144
	v_max_f32_e32 v198, v137, v137
	v_max_f32_e32 v199, v136, v136
	v_max_f32_e32 v190, v191, v190
	v_max_f32_e32 v198, v199, v198
	v_max3_f32 v190, v190, v146, v147
	v_max3_f32 v198, v198, v138, v139
	v_max3_f32 v190, v190, v140, v141
	v_max3_f32 v198, v198, v132, v133
	v_max3_f32 v190, v190, v142, v143
	v_max3_f32 v198, v198, v134, v135
	v_mov_b32_e32 v191, v190
	v_mov_b32_e32 v199, v198
	s_nop 1
	v_permlane16_swap_b32_e32 v191, v190
	v_permlane16_swap_b32_e32 v199, v198
	v_max_f32_e32 v190, v190, v191
	v_max_f32_e32 v198, v198, v199
	v_mov_b32_e32 v191, v190
	v_mov_b32_e32 v199, v198
	s_nop 1
	v_permlane32_swap_b32_e32 v191, v190
	v_permlane32_swap_b32_e32 v199, v198
	v_max_f32_e32 v213, v190, v191
	v_max_f32_e32 v200, v198, v199
	v_cmp_lt_f32_e32 vcc, s79, v213
	s_cbranch_vccz .LBB0_379
	s_nop 0
	v_cndmask_b32_e32 v191, 0, v213, vcc
	v_exp_f32_e64 v190, -v191
	v_add_f32_e32 v187, v187, v191
	v_sub_f32_e32 v144, v144, v191
	v_sub_f32_e32 v145, v145, v191
	v_pk_mul_f32 v[70:71], v[70:71], v[190:191] op_sel_hi:[1,0]
	v_pk_mul_f32 v[68:69], v[68:69], v[190:191] op_sel_hi:[1,0]
	v_pk_mul_f32 v[74:75], v[74:75], v[190:191] op_sel_hi:[1,0]
	v_pk_mul_f32 v[72:73], v[72:73], v[190:191] op_sel_hi:[1,0]
	v_pk_mul_f32 v[78:79], v[78:79], v[190:191] op_sel_hi:[1,0]
	v_pk_mul_f32 v[76:77], v[76:77], v[190:191] op_sel_hi:[1,0]
	v_pk_mul_f32 v[102:103], v[102:103], v[190:191] op_sel_hi:[1,0]
	v_pk_mul_f32 v[100:101], v[100:101], v[190:191] op_sel_hi:[1,0]
	v_pk_mul_f32 v[82:83], v[82:83], v[190:191] op_sel_hi:[1,0]
	v_pk_mul_f32 v[80:81], v[80:81], v[190:191] op_sel_hi:[1,0]
	v_pk_mul_f32 v[106:107], v[106:107], v[190:191] op_sel_hi:[1,0]
	v_pk_mul_f32 v[104:105], v[104:105], v[190:191] op_sel_hi:[1,0]
	v_pk_mul_f32 v[110:111], v[110:111], v[190:191] op_sel_hi:[1,0]
	v_pk_mul_f32 v[108:109], v[108:109], v[190:191] op_sel_hi:[1,0]
	v_pk_mul_f32 v[86:87], v[86:87], v[190:191] op_sel_hi:[1,0]
	v_pk_mul_f32 v[84:85], v[84:85], v[190:191] op_sel_hi:[1,0]
	v_mul_f32_e32 v165, v165, v190
	v_sub_f32_e32 v146, v146, v191
	v_sub_f32_e32 v147, v147, v191
	v_sub_f32_e32 v140, v140, v191
	v_sub_f32_e32 v141, v141, v191
	v_sub_f32_e32 v142, v142, v191
	v_sub_f32_e32 v143, v143, v191
